# per-XCD barrier (no L2 write-back / cross-XCD hop) after gu, branch and gu2 GEMM phases whose consumers are row-local
# baseline (speedup 1.0000x reference)
; __device__ __forceinline__ unsigned xb_ld(unsigned* p)              { return __hip_atomic_load(p, __ATOMIC_RELAXED, __HIP_MEMORY_SCOPE_AGENT); }
; __device__ __forceinline__ unsigned xb_add(unsigned* p, unsigned v) { return __hip_atomic_fetch_add(p, v, __ATOMIC_RELAXED, __HIP_MEMORY_SCOPE_AGENT); }
; #define XB_SPIN(cond, bar) do { unsigned _sp = 0; while (cond) { __builtin_amdgcn_s_sleep(1); \
;     if ((++_sp & 255u) == 0u) { if (xb_ld(&(bar)[XB_TMO])) break; if (_sp > XB_SPIN_CAP) { atomicAdd(&(bar)[XB_TMO], 1u); break; } } } } while (0)
; __device__ __forceinline__ void xcd_barrier(const XcdBarrier& b) {
;     ...
;         const unsigned old = xb_add(&bar[XB_XSUB(b.x)], 1u);
;         const unsigned gen = old / nloc;
;         if (old + 1u == (gen + 1u) * nloc) {
;             __builtin_amdgcn_fence(__ATOMIC_RELEASE, "agent");
;             asm volatile("s_waitcnt vmcnt(0)" ::: "memory");
;             const unsigned og = xb_add(&bar[XB_TOP], 1u);
;             const unsigned tg = og / nx;
;             if (og + 1u == (tg + 1u) * nx) xb_add(&bar[XB_TOPGEN], 1u);
;             else XB_SPIN(xb_ld(&bar[XB_TOPGEN]) == tg, bar);
;             __builtin_amdgcn_fence(__ATOMIC_ACQUIRE, "agent");
;             xb_add(&bar[XB_XGEN(b.x)], 1u);
;             asm volatile("s_waitcnt vmcnt(0)" ::: "memory");
;         } else {
;             XB_SPIN(xb_ld(&bar[XB_XGEN(b.x)]) == gen, bar);
;             __builtin_amdgcn_fence(__ATOMIC_ACQUIRE, "agent");
;             asm volatile("s_waitcnt vmcnt(0)" ::: "memory");
;         }
.LBB0_185:
	s_andn2_saveexec_b64 s[2:3], s[2:3]
	s_cbranch_execz .LBB0_203
	s_waitcnt vmcnt(0) lgkmcnt(0)
	buffer_inv sc1
	global_atomic_add v[196:197], v241, off
	s_waitcnt vmcnt(0)
